# merge + out GEMM K-loops: flips deleted, static s_setprio 1 for waves 0-3 (same as proj GEMM)
# baseline (speedup 1.0000x reference)
; #define LAS __attribute__((address_space(3)))
; #define P_rstd   WSP(float, WS_RSTD)
;     DI bool next(int i, Unit& u) const {
;         const long L = (long)i * G + c; if (L >= nwg) return false;
;         int wgid = (int)L; { const int q = nwg / NXCD, r = nwg % NXCD, xcd = wgid % NXCD, off = wgid / NXCD; wgid = (xcd < r ? xcd * (q + 1) : r * (q + 1) + (xcd - r) * q) + off; }
;         const int nig = WGM * nN, gid = wgid / nig, fm = gid * WGM, gsz = (nM - fm) < WGM ? (nM - fm) : WGM;
;         u.pm = fm + ((wgid % nig) % gsz); u.pn = (wgid % nig) / gsz; return true;
; template <int PH>
; DI void run_phase(const Params& P, unsigned char* smem) {
;     ...
;         S.init(NTOK, DM, gridDim.x, blockIdx.x);
;         pg8::Gemm gm{P_yg, P_wossdT, NTOK, DM, 4096, 4096, 4096}; pg8::EpiMergeF E{P_proj, P_rstd}; pg8::gemm_phase((LAS unsigned char*)smem, gm, S, E);
.LBB0_614:
	s_or_b64 exec, exec, s[2:3]
	v_mov_b32_e32 v1, v215
	s_cmpk_lt_i32 s6, 0x400
	s_waitcnt lgkmcnt(0)
	s_barrier
	s_cselect_b64 s[4:5], -1, 0
	s_cmpk_gt_i32 s6, 0x3ff
	v_readfirstlane_b32 s42, v1
	s_cbranch_scc1 .LBB0_636
	s_nop 1
	s_cmpk_ge_u32 s42, 0x100
	s_cbranch_scc1 .Lp4_prio_done
	s_setprio 1
.Lp4_prio_done:
	s_ashr_i32 s43, s6, 31
	s_lshr_b32 s0, s43, 29
	s_add_i32 s9, s6, s0
	s_and_b32 s0, s9, -8
	s_sub_i32 s16, s6, s0
	s_cmp_gt_i32 s16, -1
	s_cbranch_scc0 .LBB0_617
	s_lshl_b32 s8, s16, 7
	s_cbranch_execz .LBB0_618
	s_branch .LBB0_619

; #define PG8_STAGE(bufoff, gbase, voff) do { _Pragma("unroll") for (int _i = 0; _i < 2; ++_i) \
;         __builtin_amdgcn_global_load_lds((const unsigned*)((const char*)(gbase) + (voff)[_i]), (LAS unsigned*)(lds + (bufoff) + ldsw + _i * 8192), 16, 0, 0); } while (0)
; #define PG8_LDA(dst, b, h) do { _Pragma("unroll") for (int m = 0; m < 4; ++m) _Pragma("unroll") for (int k = 0; k < 2; ++k) dst[m][k] = *(const LAS bf16x8*)(lds + PG8_SA(b, h) + aoff + m * 2048 + k * 1024); } while (0)
; #define PG8_LDB(dst, b, h) do { _Pragma("unroll") for (int n = 0; n < 2; ++n) _Pragma("unroll") for (int k = 0; k < 2; ++k) dst[n][k] = *(const LAS bf16x8*)(lds + PG8_SB(b, h) + boff + n * 2048 + k * 1024); } while (0)
; #define PG8_MMA(ai, bj, At, Bt) do { __builtin_amdgcn_s_setprio(1); _Pragma("unroll") for (int m = 0; m < 4; ++m) _Pragma("unroll") for (int n = 0; n < 2; ++n) _Pragma("unroll") for (int k = 0; k < 2; ++k) \
;         acc[ai][bj][m][n] = __builtin_amdgcn_mfma_f32_16x16x32_bf16(Bt[n][k], At[m][k], acc[ai][bj][m][n], 0, 0, 0); __builtin_amdgcn_s_setprio(0); } while (0)
; #define PG8_WAIT_L(n) asm volatile("s_waitcnt lgkmcnt(" #n ")" ::: "memory")
; #define PG8_BAR __builtin_amdgcn_s_barrier()
; #define PG8_SCHED __builtin_amdgcn_sched_barrier(0)
; template <class Epi>
; DI void gemm_phase(LAS unsigned char* lds, const Gemm g, const StaticOrder& S, const Epi& E) {
;     ...
;         for (int t = 0; t < nt; t += 2) {
;             const bool last = (t == nt - 2);
;             const char* a1 = cA + (size_t)(t + 1) * kstep;
;             const char* a2 = last ? nA : cA + (size_t)(t + 2) * kstep; const char* b2 = last ? nB : cB + (size_t)(t + 2) * kstep;
;             const char* a3 = a2 + kstep; const char* b3 = b2 + kstep;
;             if constexpr (Epi::HAS_MID) { if (t == Epi::MID_T) E.mid(acc, cur, wr, wc, fr, fq); }
;             PG8_LDB(B0, 0, 0); PG8_SCHED; PG8_LDA(At, 0, 0); PG8_STAGE(PG8_SA(1, 1), a1 + hstepA, voffA);
;             PG8_WAIT_L(8); PG8_BAR; PG8_WAIT_L(0); PG8_MMA(0, 0, At, B0); PG8_BAR; PG8_SCHED;
;             PG8_LDB(B1, 0, 1); PG8_STAGE(PG8_SB(0, 0), b2, voffB);
;             PG8_BAR; PG8_WAIT_L(0); PG8_MMA(0, 1, At, B1); PG8_BAR;
;             PG8_LDA(At, 0, 1); PG8_STAGE(PG8_SA(0, 0), a2, voffA);
;             PG8_BAR; PG8_WAIT_L(0); PG8_MMA(1, 0, At, B0); PG8_BAR; PG8_SCHED;
.LBB0_630:
	v_add_u32_e32 v1, s56, v219
	s_add_u32 s0, s26, s36
	ds_read_b128 v[132:135], v1
	ds_read_b128 v[136:139], v1 offset:1024
	ds_read_b128 v[140:143], v1 offset:2048
	ds_read_b128 v[144:147], v1 offset:3072
	s_addc_u32 s1, s27, s37
	s_add_u32 s0, s0, 0x100
	s_addc_u32 s1, s1, 0
	s_add_u32 s38, s60, s36
	s_addc_u32 s39, s61, s37
	s_cmpk_eq_i32 s36, 0x1f00
	s_cselect_b32 s41, s21, s1
	s_cselect_b32 s40, s58, s0
	s_cselect_b32 s39, s19, s39
	s_cselect_b32 s38, s59, s38
	v_lshl_add_u64 v[2:3], v[206:207], 0, s[36:37]
	s_add_i32 m0, s44, 0xc000
	ds_read_b128 v[148:151], v222
	ds_read_b128 v[152:155], v222 offset:1024
	ds_read_b128 v[156:159], v222 offset:2048
	s_waitcnt vmcnt(0)
	ds_read_b128 v[160:163], v222 offset:3072
	ds_read_b128 v[164:167], v222 offset:4096
	ds_read_b128 v[168:171], v222 offset:5120
	ds_read_b128 v[172:175], v222 offset:6144
	ds_read_b128 v[176:179], v222 offset:7168
	global_load_lds_dwordx4 v[2:3], off
	v_lshl_add_u64 v[2:3], v[208:209], 0, s[36:37]
	s_add_i32 m0, s44, 0xe000
	s_nop 0
	global_load_lds_dwordx4 v[2:3], off
	s_waitcnt lgkmcnt(8)
	s_barrier
	s_waitcnt lgkmcnt(0)
	s_waitcnt lgkmcnt(0)
	v_mfma_f32_16x16x32_bf16 v[128:131], v[132:135], v[148:151], v[128:131]
	v_mfma_f32_16x16x32_bf16 v[124:127], v[140:143], v[148:151], v[124:127]
	v_mfma_f32_16x16x32_bf16 v[112:115], v[132:135], v[156:159], v[112:115]
	v_mfma_f32_16x16x32_bf16 v[108:111], v[140:143], v[156:159], v[108:111]
	v_mfma_f32_16x16x32_bf16 v[96:99], v[132:135], v[164:167], v[96:99]
	v_mfma_f32_16x16x32_bf16 v[92:95], v[140:143], v[164:167], v[92:95]
	v_mfma_f32_16x16x32_bf16 v[80:83], v[132:135], v[172:175], v[80:83]
	v_mfma_f32_16x16x32_bf16 v[76:79], v[140:143], v[172:175], v[76:79]
	v_mfma_f32_16x16x32_bf16 v[128:131], v[136:139], v[152:155], v[128:131]
	v_mfma_f32_16x16x32_bf16 v[124:127], v[144:147], v[152:155], v[124:127]
	v_mfma_f32_16x16x32_bf16 v[112:115], v[136:139], v[160:163], v[112:115]
	v_mfma_f32_16x16x32_bf16 v[108:111], v[144:147], v[160:163], v[108:111]
	v_mfma_f32_16x16x32_bf16 v[96:99], v[136:139], v[168:171], v[96:99]
	v_mfma_f32_16x16x32_bf16 v[92:95], v[144:147], v[168:171], v[92:95]
	v_mfma_f32_16x16x32_bf16 v[80:83], v[136:139], v[176:179], v[80:83]
	v_mfma_f32_16x16x32_bf16 v[76:79], v[144:147], v[176:179], v[76:79]
	s_barrier
	s_add_i32 s0, s56, s33
	v_add_u32_e32 v1, s57, v219
	v_lshl_add_u64 v[228:229], s[38:39], 0, v[190:191]
	s_mov_b32 m0, s0
	ds_read_b128 v[180:183], v1
	ds_read_b128 v[184:187], v1 offset:1024
	ds_read_b128 v[210:213], v1 offset:2048
	ds_read_b128 v[224:227], v1 offset:3072
	global_load_lds_dwordx4 v[228:229], off
	v_lshl_add_u64 v[230:231], s[38:39], 0, v[194:195]
	s_add_i32 m0, s0, 0x2000
	s_nop 0
	global_load_lds_dwordx4 v[230:231], off
	s_barrier
	s_waitcnt lgkmcnt(0)
	s_waitcnt lgkmcnt(0)
	v_mfma_f32_16x16x32_bf16 v[120:123], v[180:183], v[148:151], v[120:123]
	v_mfma_f32_16x16x32_bf16 v[116:119], v[210:213], v[148:151], v[116:119]
	v_mfma_f32_16x16x32_bf16 v[104:107], v[180:183], v[156:159], v[104:107]
	v_mfma_f32_16x16x32_bf16 v[100:103], v[210:213], v[156:159], v[100:103]
	v_mfma_f32_16x16x32_bf16 v[88:91], v[180:183], v[164:167], v[88:91]
	v_mfma_f32_16x16x32_bf16 v[84:87], v[210:213], v[164:167], v[84:87]
	v_mfma_f32_16x16x32_bf16 v[72:75], v[180:183], v[172:175], v[72:75]
	v_mfma_f32_16x16x32_bf16 v[68:71], v[210:213], v[172:175], v[68:71]
	v_mfma_f32_16x16x32_bf16 v[120:123], v[184:187], v[152:155], v[120:123]
	v_mfma_f32_16x16x32_bf16 v[116:119], v[224:227], v[152:155], v[116:119]
	v_mfma_f32_16x16x32_bf16 v[104:107], v[184:187], v[160:163], v[104:107]
	v_mfma_f32_16x16x32_bf16 v[100:103], v[224:227], v[160:163], v[100:103]
	v_mfma_f32_16x16x32_bf16 v[88:91], v[184:187], v[168:171], v[88:91]
	v_mfma_f32_16x16x32_bf16 v[84:87], v[224:227], v[168:171], v[84:87]
	v_mfma_f32_16x16x32_bf16 v[72:75], v[184:187], v[176:179], v[72:75]
	v_mfma_f32_16x16x32_bf16 v[68:71], v[224:227], v[176:179], v[68:71]
	s_mov_b32 m0, s44
	v_lshl_add_u64 v[232:233], s[40:41], 0, v[188:189]
	s_barrier
	ds_read_b128 v[148:151], v222 offset:16384
	ds_read_b128 v[152:155], v222 offset:17408
	ds_read_b128 v[156:159], v222 offset:18432
	ds_read_b128 v[160:163], v222 offset:19456
	ds_read_b128 v[164:167], v222 offset:20480
	ds_read_b128 v[168:171], v222 offset:21504
	ds_read_b128 v[172:175], v222 offset:22528
	ds_read_b128 v[176:179], v222 offset:23552
	global_load_lds_dwordx4 v[232:233], off
	v_lshl_add_u64 v[234:235], s[40:41], 0, v[192:193]
	s_mov_b32 m0, s45
	s_nop 0
	global_load_lds_dwordx4 v[234:235], off
	s_barrier
	s_waitcnt lgkmcnt(0)
	s_waitcnt lgkmcnt(0)
	v_mfma_f32_16x16x32_bf16 v[64:67], v[132:135], v[148:151], v[64:67]
	v_mfma_f32_16x16x32_bf16 v[60:63], v[140:143], v[148:151], v[60:63]
	v_mfma_f32_16x16x32_bf16 v[48:51], v[132:135], v[156:159], v[48:51]
	v_mfma_f32_16x16x32_bf16 v[44:47], v[140:143], v[156:159], v[44:47]
	v_mfma_f32_16x16x32_bf16 v[32:35], v[132:135], v[164:167], v[32:35]
	v_mfma_f32_16x16x32_bf16 v[28:31], v[140:143], v[164:167], v[28:31]
	v_mfma_f32_16x16x32_bf16 v[16:19], v[132:135], v[172:175], v[16:19]
	v_mfma_f32_16x16x32_bf16 v[12:15], v[140:143], v[172:175], v[12:15]
	v_mfma_f32_16x16x32_bf16 v[64:67], v[136:139], v[152:155], v[64:67]
	v_mfma_f32_16x16x32_bf16 v[60:63], v[144:147], v[152:155], v[60:63]
	v_mfma_f32_16x16x32_bf16 v[48:51], v[136:139], v[160:163], v[48:51]
	v_mfma_f32_16x16x32_bf16 v[44:47], v[144:147], v[160:163], v[44:47]
	v_mfma_f32_16x16x32_bf16 v[32:35], v[136:139], v[168:171], v[32:35]
	v_mfma_f32_16x16x32_bf16 v[28:31], v[144:147], v[168:171], v[28:31]
	v_mfma_f32_16x16x32_bf16 v[16:19], v[136:139], v[176:179], v[16:19]
	v_mfma_f32_16x16x32_bf16 v[12:15], v[144:147], v[176:179], v[12:15]
	s_barrier
; #define PG8_STAGE(bufoff, gbase, voff) do { _Pragma("unroll") for (int _i = 0; _i < 2; ++_i) \
;         __builtin_amdgcn_global_load_lds((const unsigned*)((const char*)(gbase) + (voff)[_i]), (LAS unsigned*)(lds + (bufoff) + ldsw + _i * 8192), 16, 0, 0); } while (0)
; #define PG8_LDA(dst, b, h) do { _Pragma("unroll") for (int m = 0; m < 4; ++m) _Pragma("unroll") for (int k = 0; k < 2; ++k) dst[m][k] = *(const LAS bf16x8*)(lds + PG8_SA(b, h) + aoff + m * 2048 + k * 1024); } while (0)
; #define PG8_LDB(dst, b, h) do { _Pragma("unroll") for (int n = 0; n < 2; ++n) _Pragma("unroll") for (int k = 0; k < 2; ++k) dst[n][k] = *(const LAS bf16x8*)(lds + PG8_SB(b, h) + boff + n * 2048 + k * 1024); } while (0)
; #define PG8_MMA(ai, bj, At, Bt) do { __builtin_amdgcn_s_setprio(1); _Pragma("unroll") for (int m = 0; m < 4; ++m) _Pragma("unroll") for (int n = 0; n < 2; ++n) _Pragma("unroll") for (int k = 0; k < 2; ++k) \
;         acc[ai][bj][m][n] = __builtin_amdgcn_mfma_f32_16x16x32_bf16(Bt[n][k], At[m][k], acc[ai][bj][m][n], 0, 0, 0); __builtin_amdgcn_s_setprio(0); } while (0)
; #define PG8_WAIT_V(n) asm volatile("s_waitcnt vmcnt(" #n ")" ::: "memory")
; #define PG8_WAIT_L(n) asm volatile("s_waitcnt lgkmcnt(" #n ")" ::: "memory")
; #define PG8_BAR __builtin_amdgcn_s_barrier()
; #define PG8_SCHED __builtin_amdgcn_sched_barrier(0)
; template <class Epi>
; DI void gemm_phase(LAS unsigned char* lds, const Gemm g, const StaticOrder& S, const Epi& E) {
;     ...
;             PG8_STAGE(PG8_SB(0, 1), b2 + hstepB, voffB);
;             PG8_WAIT_V(6); PG8_BAR; PG8_MMA(1, 1, At, B1); PG8_BAR;
;             PG8_LDB(B0, 1, 0); PG8_SCHED; PG8_LDA(At, 1, 0); PG8_STAGE(PG8_SA(0, 1), a2 + hstepA, voffA);
;             PG8_WAIT_L(8); PG8_BAR; PG8_WAIT_L(0); PG8_MMA(0, 0, At, B0); PG8_BAR; PG8_SCHED;
;             PG8_LDB(B1, 1, 1); PG8_STAGE(PG8_SB(1, 0), b3, voffB);
;             PG8_BAR; PG8_WAIT_L(0); PG8_MMA(0, 1, At, B1); PG8_BAR;
;             PG8_LDA(At, 1, 1); PG8_STAGE(PG8_SA(1, 0), a3, voffA);
;             PG8_BAR; PG8_WAIT_L(0); PG8_MMA(1, 0, At, B0); PG8_BAR; PG8_SCHED;
	s_add_u32 s0, s38, 0x100000
	s_addc_u32 s1, s39, 0
	s_add_i32 s63, s57, s33
	v_lshl_add_u64 v[2:3], s[0:1], 0, v[190:191]
	s_mov_b32 m0, s63
	s_nop 0
	global_load_lds_dwordx4 v[2:3], off
	v_lshl_add_u64 v[2:3], s[0:1], 0, v[194:195]
	s_add_i32 m0, s63, 0x2000
	s_nop 0
	global_load_lds_dwordx4 v[2:3], off
	s_waitcnt vmcnt(6)
	s_barrier
	v_mfma_f32_16x16x32_bf16 v[56:59], v[180:183], v[148:151], v[56:59]
	v_mfma_f32_16x16x32_bf16 v[52:55], v[210:213], v[148:151], v[52:55]
	v_mfma_f32_16x16x32_bf16 v[40:43], v[180:183], v[156:159], v[40:43]
	v_mfma_f32_16x16x32_bf16 v[36:39], v[210:213], v[156:159], v[36:39]
	v_mfma_f32_16x16x32_bf16 v[24:27], v[180:183], v[164:167], v[24:27]
	v_mfma_f32_16x16x32_bf16 v[20:23], v[210:213], v[164:167], v[20:23]
	v_mfma_f32_16x16x32_bf16 v[8:11], v[180:183], v[172:175], v[8:11]
	v_mfma_f32_16x16x32_bf16 v[2:5], v[210:213], v[172:175], v[4:7]
	v_mfma_f32_16x16x32_bf16 v[56:59], v[184:187], v[152:155], v[56:59]
	v_mfma_f32_16x16x32_bf16 v[52:55], v[224:227], v[152:155], v[52:55]
	v_mfma_f32_16x16x32_bf16 v[40:43], v[184:187], v[160:163], v[40:43]
	v_mfma_f32_16x16x32_bf16 v[36:39], v[224:227], v[160:163], v[36:39]
	v_mfma_f32_16x16x32_bf16 v[24:27], v[184:187], v[168:171], v[24:27]
	v_mfma_f32_16x16x32_bf16 v[20:23], v[224:227], v[168:171], v[20:23]
	v_mfma_f32_16x16x32_bf16 v[8:11], v[184:187], v[176:179], v[8:11]
	v_mfma_f32_16x16x32_bf16 v[2:5], v[224:227], v[176:179], v[2:5]
	s_add_i32 s63, 0, 0x18000
	v_add_u32_e32 v1, s63, v219
	s_barrier
	ds_read_b128 v[132:135], v1
	ds_read_b128 v[136:139], v1 offset:1024
	ds_read_b128 v[140:143], v1 offset:2048
	ds_read_b128 v[144:147], v1 offset:3072
	s_add_u32 s0, s40, 0x100000
	s_addc_u32 s1, s41, 0
	s_mov_b32 m0, s46
	v_lshl_add_u64 v[6:7], s[0:1], 0, v[188:189]
	ds_read_b128 v[148:151], v222 offset:32768
	ds_read_b128 v[152:155], v222 offset:33792
	ds_read_b128 v[156:159], v222 offset:34816
	ds_read_b128 v[160:163], v222 offset:35840
	ds_read_b128 v[164:167], v222 offset:36864
	ds_read_b128 v[168:171], v222 offset:37888
	ds_read_b128 v[172:175], v222 offset:38912
	ds_read_b128 v[176:179], v222 offset:39936
	global_load_lds_dwordx4 v[6:7], off
	v_lshl_add_u64 v[6:7], s[0:1], 0, v[192:193]
	s_mov_b32 m0, s47
	s_nop 0
	global_load_lds_dwordx4 v[6:7], off
	s_waitcnt lgkmcnt(8)
	s_barrier
	s_waitcnt lgkmcnt(0)
	s_waitcnt lgkmcnt(0)
	v_mfma_f32_16x16x32_bf16 v[128:131], v[132:135], v[148:151], v[128:131]
	v_mfma_f32_16x16x32_bf16 v[124:127], v[140:143], v[148:151], v[124:127]
	v_mfma_f32_16x16x32_bf16 v[112:115], v[132:135], v[156:159], v[112:115]
	v_mfma_f32_16x16x32_bf16 v[108:111], v[140:143], v[156:159], v[108:111]
	v_mfma_f32_16x16x32_bf16 v[96:99], v[132:135], v[164:167], v[96:99]
	v_mfma_f32_16x16x32_bf16 v[92:95], v[140:143], v[164:167], v[92:95]
	v_mfma_f32_16x16x32_bf16 v[80:83], v[132:135], v[172:175], v[80:83]
	v_mfma_f32_16x16x32_bf16 v[76:79], v[140:143], v[172:175], v[76:79]
	v_mfma_f32_16x16x32_bf16 v[128:131], v[136:139], v[152:155], v[128:131]
	v_mfma_f32_16x16x32_bf16 v[124:127], v[144:147], v[152:155], v[124:127]
	v_mfma_f32_16x16x32_bf16 v[112:115], v[136:139], v[160:163], v[112:115]
	v_mfma_f32_16x16x32_bf16 v[108:111], v[144:147], v[160:163], v[108:111]
	v_mfma_f32_16x16x32_bf16 v[96:99], v[136:139], v[168:171], v[96:99]
	v_mfma_f32_16x16x32_bf16 v[92:95], v[144:147], v[168:171], v[92:95]
	v_mfma_f32_16x16x32_bf16 v[80:83], v[136:139], v[176:179], v[80:83]
	v_mfma_f32_16x16x32_bf16 v[76:79], v[144:147], v[176:179], v[76:79]
	s_barrier
	s_add_i32 s40, 0, 0x1c000
	s_add_i32 s0, s63, s33
	v_add_u32_e32 v1, s40, v219
	v_lshl_add_u64 v[6:7], v[228:229], 0, s[16:17]
	s_mov_b32 m0, s0
	ds_read_b128 v[180:183], v1
	ds_read_b128 v[184:187], v1 offset:1024
	ds_read_b128 v[210:213], v1 offset:2048
	ds_read_b128 v[224:227], v1 offset:3072
	global_load_lds_dwordx4 v[6:7], off
	v_lshl_add_u64 v[6:7], v[230:231], 0, s[16:17]
	s_add_i32 m0, s0, 0x2000
	s_nop 0
	global_load_lds_dwordx4 v[6:7], off
	s_barrier
; #define PG8_STAGE(bufoff, gbase, voff) do { _Pragma("unroll") for (int _i = 0; _i < 2; ++_i) \
;         __builtin_amdgcn_global_load_lds((const unsigned*)((const char*)(gbase) + (voff)[_i]), (LAS unsigned*)(lds + (bufoff) + ldsw + _i * 8192), 16, 0, 0); } while (0)
; #define PG8_LDA(dst, b, h) do { _Pragma("unroll") for (int m = 0; m < 4; ++m) _Pragma("unroll") for (int k = 0; k < 2; ++k) dst[m][k] = *(const LAS bf16x8*)(lds + PG8_SA(b, h) + aoff + m * 2048 + k * 1024); } while (0)
; #define PG8_LDB(dst, b, h) do { _Pragma("unroll") for (int n = 0; n < 2; ++n) _Pragma("unroll") for (int k = 0; k < 2; ++k) dst[n][k] = *(const LAS bf16x8*)(lds + PG8_SB(b, h) + boff + n * 2048 + k * 1024); } while (0)
; #define PG8_MMA(ai, bj, At, Bt) do { __builtin_amdgcn_s_setprio(1); _Pragma("unroll") for (int m = 0; m < 4; ++m) _Pragma("unroll") for (int n = 0; n < 2; ++n) _Pragma("unroll") for (int k = 0; k < 2; ++k) \
;         acc[ai][bj][m][n] = __builtin_amdgcn_mfma_f32_16x16x32_bf16(Bt[n][k], At[m][k], acc[ai][bj][m][n], 0, 0, 0); __builtin_amdgcn_s_setprio(0); } while (0)
; #define PG8_WAIT_V(n) asm volatile("s_waitcnt vmcnt(" #n ")" ::: "memory")
; #define PG8_WAIT_L(n) asm volatile("s_waitcnt lgkmcnt(" #n ")" ::: "memory")
; #define PG8_BAR __builtin_amdgcn_s_barrier()
; #define PG8_SCHED __builtin_amdgcn_sched_barrier(0)
; template <class Epi>
; DI void gemm_phase(LAS unsigned char* lds, const Gemm g, const StaticOrder& S, const Epi& E) {
;     ...
;             PG8_LDB(B1, 1, 1); PG8_STAGE(PG8_SB(1, 0), b3, voffB);
;             PG8_BAR; PG8_WAIT_L(0); PG8_MMA(0, 1, At, B1); PG8_BAR;
;             PG8_LDA(At, 1, 1); PG8_STAGE(PG8_SA(1, 0), a3, voffA);
;             PG8_BAR; PG8_WAIT_L(0); PG8_MMA(1, 0, At, B0); PG8_BAR; PG8_SCHED;
;             PG8_STAGE(PG8_SB(1, 1), b3 + hstepB, voffB);
;             PG8_WAIT_V(6); PG8_BAR; PG8_MMA(1, 1, At, B1); PG8_BAR;
	s_waitcnt lgkmcnt(0)
	s_waitcnt lgkmcnt(0)
	v_mfma_f32_16x16x32_bf16 v[120:123], v[180:183], v[148:151], v[120:123]
	v_mfma_f32_16x16x32_bf16 v[116:119], v[210:213], v[148:151], v[116:119]
	v_mfma_f32_16x16x32_bf16 v[104:107], v[180:183], v[156:159], v[104:107]
	v_mfma_f32_16x16x32_bf16 v[100:103], v[210:213], v[156:159], v[100:103]
	v_mfma_f32_16x16x32_bf16 v[88:91], v[180:183], v[164:167], v[88:91]
	v_mfma_f32_16x16x32_bf16 v[84:87], v[210:213], v[164:167], v[84:87]
	v_mfma_f32_16x16x32_bf16 v[72:75], v[180:183], v[172:175], v[72:75]
	v_mfma_f32_16x16x32_bf16 v[68:71], v[210:213], v[172:175], v[68:71]
	v_mfma_f32_16x16x32_bf16 v[120:123], v[184:187], v[152:155], v[120:123]
	v_mfma_f32_16x16x32_bf16 v[116:119], v[224:227], v[152:155], v[116:119]
	v_mfma_f32_16x16x32_bf16 v[104:107], v[184:187], v[160:163], v[104:107]
	v_mfma_f32_16x16x32_bf16 v[100:103], v[224:227], v[160:163], v[100:103]
	v_mfma_f32_16x16x32_bf16 v[88:91], v[184:187], v[168:171], v[88:91]
	v_mfma_f32_16x16x32_bf16 v[84:87], v[224:227], v[168:171], v[84:87]
	v_mfma_f32_16x16x32_bf16 v[72:75], v[184:187], v[176:179], v[72:75]
	v_mfma_f32_16x16x32_bf16 v[68:71], v[224:227], v[176:179], v[68:71]
	s_mov_b32 m0, s50
	v_lshl_add_u64 v[6:7], v[232:233], 0, s[16:17]
	s_barrier
	ds_read_b128 v[148:151], v222 offset:49152
	ds_read_b128 v[152:155], v222 offset:50176
	ds_read_b128 v[156:159], v222 offset:51200
	ds_read_b128 v[160:163], v222 offset:52224
	ds_read_b128 v[164:167], v222 offset:53248
	ds_read_b128 v[168:171], v222 offset:54272
	ds_read_b128 v[172:175], v222 offset:55296
	ds_read_b128 v[176:179], v222 offset:56320
	global_load_lds_dwordx4 v[6:7], off
	v_lshl_add_u64 v[6:7], v[234:235], 0, s[16:17]
	s_mov_b32 m0, s51
	s_nop 0
	global_load_lds_dwordx4 v[6:7], off
	s_barrier
	s_waitcnt lgkmcnt(0)
	s_waitcnt lgkmcnt(0)
	v_mfma_f32_16x16x32_bf16 v[64:67], v[132:135], v[148:151], v[64:67]
	v_mfma_f32_16x16x32_bf16 v[60:63], v[140:143], v[148:151], v[60:63]
	v_mfma_f32_16x16x32_bf16 v[48:51], v[132:135], v[156:159], v[48:51]
	v_mfma_f32_16x16x32_bf16 v[44:47], v[140:143], v[156:159], v[44:47]
	v_mfma_f32_16x16x32_bf16 v[32:35], v[132:135], v[164:167], v[32:35]
	v_mfma_f32_16x16x32_bf16 v[28:31], v[140:143], v[164:167], v[28:31]
	v_mfma_f32_16x16x32_bf16 v[16:19], v[132:135], v[172:175], v[16:19]
	v_mfma_f32_16x16x32_bf16 v[12:15], v[140:143], v[172:175], v[12:15]
	v_mfma_f32_16x16x32_bf16 v[64:67], v[136:139], v[152:155], v[64:67]
	v_mfma_f32_16x16x32_bf16 v[60:63], v[144:147], v[152:155], v[60:63]
	v_mfma_f32_16x16x32_bf16 v[48:51], v[136:139], v[160:163], v[48:51]
	v_mfma_f32_16x16x32_bf16 v[44:47], v[144:147], v[160:163], v[44:47]
	v_mfma_f32_16x16x32_bf16 v[32:35], v[136:139], v[168:171], v[32:35]
	v_mfma_f32_16x16x32_bf16 v[28:31], v[144:147], v[168:171], v[28:31]
	v_mfma_f32_16x16x32_bf16 v[16:19], v[136:139], v[176:179], v[16:19]
	v_mfma_f32_16x16x32_bf16 v[12:15], v[144:147], v[176:179], v[12:15]
	s_barrier
	s_add_u32 s0, s38, 0x100080
	s_addc_u32 s1, s39, 0
	s_add_i32 s38, s40, s33
	v_lshl_add_u64 v[6:7], s[0:1], 0, v[190:191]
	s_mov_b32 m0, s38
	s_nop 0
	global_load_lds_dwordx4 v[6:7], off
	v_lshl_add_u64 v[6:7], s[0:1], 0, v[194:195]
	s_add_i32 m0, s38, 0x2000
	s_nop 0
	global_load_lds_dwordx4 v[6:7], off
	s_waitcnt vmcnt(6)
	s_barrier
	v_mfma_f32_16x16x32_bf16 v[56:59], v[180:183], v[148:151], v[56:59]
	v_mfma_f32_16x16x32_bf16 v[52:55], v[210:213], v[148:151], v[52:55]
	v_mfma_f32_16x16x32_bf16 v[40:43], v[180:183], v[156:159], v[40:43]
	v_mfma_f32_16x16x32_bf16 v[36:39], v[210:213], v[156:159], v[36:39]
	v_mfma_f32_16x16x32_bf16 v[24:27], v[180:183], v[164:167], v[24:27]
	v_mfma_f32_16x16x32_bf16 v[20:23], v[210:213], v[164:167], v[20:23]
	v_mfma_f32_16x16x32_bf16 v[6:9], v[180:183], v[172:175], v[8:11]
	v_mfma_f32_16x16x32_bf16 v[2:5], v[210:213], v[172:175], v[2:5]
	v_mfma_f32_16x16x32_bf16 v[56:59], v[184:187], v[152:155], v[56:59]
	v_mfma_f32_16x16x32_bf16 v[52:55], v[224:227], v[152:155], v[52:55]
	v_mfma_f32_16x16x32_bf16 v[40:43], v[184:187], v[160:163], v[40:43]
	v_mfma_f32_16x16x32_bf16 v[36:39], v[224:227], v[160:163], v[36:39]
	v_mfma_f32_16x16x32_bf16 v[24:27], v[184:187], v[168:171], v[24:27]
	v_mfma_f32_16x16x32_bf16 v[20:23], v[224:227], v[168:171], v[20:23]
	v_mfma_f32_16x16x32_bf16 v[8:11], v[184:187], v[176:179], v[6:9]
	v_mfma_f32_16x16x32_bf16 v[4:7], v[224:227], v[176:179], v[2:5]
	s_add_i32 s62, s62, 2
	s_add_u32 s36, s36, 0x100
	s_addc_u32 s37, s37, 0
	s_cmp_gt_u32 s62, 61
	s_barrier
	s_cbranch_scc1 .LBB0_622

; DI unsigned xb_ld(unsigned* p)              { return __hip_atomic_load(p, __ATOMIC_RELAXED, __HIP_MEMORY_SCOPE_AGENT); }
; DI void xcd_barrier_complete(unsigned* bar, unsigned x, unsigned& nloc, unsigned& nx) {
;     const unsigned G = gridDim.x * gridDim.y * gridDim.z;
;     unsigned sum, cnt, mine, sp = 0u;
;     for (;;) {
;         sum = 0u; cnt = 0u; mine = 0u;
; #pragma unroll
;         for (unsigned j = 0; j < 16; ++j) { const unsigned c = xb_ld(&bar[XB_XCNT(j)]); sum += c; cnt += (c > 0u) ? 1u : 0u; mine = (j == x) ? c : mine; }
; DI void xcd_barrier(const XcdBarrier& b) {
;     asm volatile("s_waitcnt vmcnt(0)" ::: "memory");
;     __syncthreads();
;     if (threadIdx.x == 0) {
;         unsigned* bar = b.bar;
;         __builtin_amdgcn_s_waitcnt(0);
;         unsigned nloc = b.st[0], nx = b.st[1];
;         if (nloc == 0u) { xcd_barrier_complete(bar, b.x, nloc, nx); b.st[0] = nloc; b.st[1] = nx; }
.LBB0_636:
	s_setprio 0
	s_waitcnt vmcnt(0)
	s_waitcnt lgkmcnt(0)
	s_barrier
	s_mov_b64 s[2:3], exec
	v_readlane_b32 s0, v236, 0
	v_readlane_b32 s1, v236, 1
	s_and_b64 s[0:1], s[2:3], s[0:1]
	s_mov_b64 exec, s[0:1]
	s_cbranch_execz .LBB0_688
	s_add_i32 s0, 0, 0x27ff0
	v_mov_b32_e32 v0, s0
	s_waitcnt vmcnt(0) expcnt(0) lgkmcnt(0)
	ds_read_b32 v2, v0
	s_add_i32 s0, 0, 0x27ff4
	v_mov_b32_e32 v0, s0
	ds_read_b32 v0, v0
	s_waitcnt lgkmcnt(1)
	v_cmp_ne_u32_e32 vcc, 0, v2
	s_cbranch_vccnz .LBB0_652
	s_add_u32 s0, s30, 0x3f732200
	s_addc_u32 s1, s31, 0
	s_add_u32 s8, s30, 0x3f732400
	s_addc_u32 s9, s31, 0
	s_add_u32 s14, s30, 0x3f732500
	s_addc_u32 s15, s31, 0
	s_add_u32 s16, s30, 0x3f732600
	s_addc_u32 s17, s31, 0
	s_add_u32 s18, s30, 0x3f732700
	s_addc_u32 s19, s31, 0
	s_add_u32 s20, s30, 0x3f732800
	s_addc_u32 s21, s31, 0
	s_add_u32 s22, s30, 0x3f732900
	s_addc_u32 s23, s31, 0
	s_add_u32 s24, s30, 0x3f732a00
	s_addc_u32 s25, s31, 0
	s_add_u32 s26, s30, 0x3f732b00
	s_addc_u32 s27, s31, 0
	s_add_u32 s36, s30, 0x3f732c00
	s_addc_u32 s37, s31, 0
	s_add_u32 s38, s30, 0x3f732d00
	s_addc_u32 s39, s31, 0
	s_add_u32 s40, s30, 0x3f732e00
	s_addc_u32 s41, s31, 0
	s_add_u32 s42, s30, 0x3f732f00
	s_addc_u32 s43, s31, 0
	s_add_u32 s44, s30, 0x3f733000
	s_addc_u32 s45, s31, 0
	s_add_u32 s46, s30, 0x3f733100
	s_addc_u32 s47, s31, 0
	s_add_u32 s48, s30, 0x3f733200
	s_addc_u32 s49, s31, 0
	s_mul_i32 s11, s11, s87
	s_add_u32 s50, s30, 0x3f733300
	s_mul_i32 s11, s11, s10
	s_addc_u32 s51, s31, 0
	s_mov_b32 s33, 1
	v_mov_b32_e32 v16, 0
	s_branch .LBB0_640

; #define LAS __attribute__((address_space(3)))
;     DI bool next(int i, Unit& u) const {
;         const long L = (long)i * G + c; if (L >= nwg) return false;
;         int wgid = (int)L; { const int q = nwg / NXCD, r = nwg % NXCD, xcd = wgid % NXCD, off = wgid / NXCD; wgid = (xcd < r ? xcd * (q + 1) : r * (q + 1) + (xcd - r) * q) + off; }
;         const int nig = WGM * nN, gid = wgid / nig, fm = gid * WGM, gsz = (nM - fm) < WGM ? (nM - fm) : WGM;
;         u.pm = fm + ((wgid % nig) % gsz); u.pn = (wgid % nig) / gsz; return true;
; template <int PH>
; DI void run_phase(const Params& P, unsigned char* smem) {
;     ...
;     else if constexpr (PH == 5) { pg8::Gemm gm{P_proj, P_woT, NTOK, DM, DM, LDP, DM}; S.init(NTOK, DM, gridDim.x, blockIdx.x); pg8::EpiOut E{P.out, P.x}; pg8::gemm_phase((LAS unsigned char*)smem, gm, S, E); }
.LBB0_688:
	s_or_b64 exec, exec, s[2:3]
	s_waitcnt lgkmcnt(0)
	s_barrier
	s_andn2_b64 vcc, exec, s[4:5]
	v_readfirstlane_b32 s7, v215
	s_cbranch_vccnz .LBB0_710
	s_nop 1
	s_cmpk_ge_u32 s7, 0x100
	s_cbranch_scc1 .Lp5_prio_done
	s_setprio 1
.Lp5_prio_done:
	s_ashr_i32 s11, s6, 31
	s_lshr_b32 s0, s11, 29
	s_add_i32 s3, s6, s0
	s_and_b32 s0, s3, -8
	s_sub_i32 s2, s6, s0
	s_cmp_gt_i32 s2, -1
	s_cbranch_scc0 .LBB0_691
	s_lshl_b32 s4, s2, 7
	s_ashr_i32 s0, s3, 3
	s_cbranch_execz .LBB0_692
	s_branch .LBB0_693

; #define PG8_STAGE(bufoff, gbase, voff) do { _Pragma("unroll") for (int _i = 0; _i < 2; ++_i) \
;         __builtin_amdgcn_global_load_lds((const unsigned*)((const char*)(gbase) + (voff)[_i]), (LAS unsigned*)(lds + (bufoff) + ldsw + _i * 8192), 16, 0, 0); } while (0)
; #define PG8_LDA(dst, b, h) do { _Pragma("unroll") for (int m = 0; m < 4; ++m) _Pragma("unroll") for (int k = 0; k < 2; ++k) dst[m][k] = *(const LAS bf16x8*)(lds + PG8_SA(b, h) + aoff + m * 2048 + k * 1024); } while (0)
; #define PG8_LDB(dst, b, h) do { _Pragma("unroll") for (int n = 0; n < 2; ++n) _Pragma("unroll") for (int k = 0; k < 2; ++k) dst[n][k] = *(const LAS bf16x8*)(lds + PG8_SB(b, h) + boff + n * 2048 + k * 1024); } while (0)
; #define PG8_MMA(ai, bj, At, Bt) do { __builtin_amdgcn_s_setprio(1); _Pragma("unroll") for (int m = 0; m < 4; ++m) _Pragma("unroll") for (int n = 0; n < 2; ++n) _Pragma("unroll") for (int k = 0; k < 2; ++k) \
;         acc[ai][bj][m][n] = __builtin_amdgcn_mfma_f32_16x16x32_bf16(Bt[n][k], At[m][k], acc[ai][bj][m][n], 0, 0, 0); __builtin_amdgcn_s_setprio(0); } while (0)
; #define PG8_WAIT_L(n) asm volatile("s_waitcnt lgkmcnt(" #n ")" ::: "memory")
; #define PG8_BAR __builtin_amdgcn_s_barrier()
; #define PG8_SCHED __builtin_amdgcn_sched_barrier(0)
; template <class Epi>
; DI void gemm_phase(LAS unsigned char* lds, const Gemm g, const StaticOrder& S, const Epi& E) {
;     ...
;         for (int t = 0; t < nt; t += 2) {
;             const bool last = (t == nt - 2);
;             const char* a1 = cA + (size_t)(t + 1) * kstep;
;             const char* a2 = last ? nA : cA + (size_t)(t + 2) * kstep; const char* b2 = last ? nB : cB + (size_t)(t + 2) * kstep;
;             const char* a3 = a2 + kstep; const char* b3 = b2 + kstep;
;             if constexpr (Epi::HAS_MID) { if (t == Epi::MID_T) E.mid(acc, cur, wr, wc, fr, fq); }
;             PG8_LDB(B0, 0, 0); PG8_SCHED; PG8_LDA(At, 0, 0); PG8_STAGE(PG8_SA(1, 1), a1 + hstepA, voffA);
;             PG8_WAIT_L(8); PG8_BAR; PG8_WAIT_L(0); PG8_MMA(0, 0, At, B0); PG8_BAR; PG8_SCHED;
;             PG8_LDB(B1, 0, 1); PG8_STAGE(PG8_SB(0, 0), b2, voffB);
;             PG8_BAR; PG8_WAIT_L(0); PG8_MMA(0, 1, At, B1); PG8_BAR;
;             PG8_LDA(At, 0, 1); PG8_STAGE(PG8_SA(0, 0), a2, voffA);
;             PG8_BAR; PG8_WAIT_L(0); PG8_MMA(1, 0, At, B0); PG8_BAR; PG8_SCHED;
.LBB0_705:
	ds_read_b128 v[144:147], v153
	ds_read_b128 v[156:159], v153 offset:1024
	ds_read_b128 v[160:163], v153 offset:2048
	ds_read_b128 v[164:167], v153 offset:3072
	s_add_u32 s2, s26, 0x100
	s_addc_u32 s3, s27, 0
	s_cmp_eq_u32 s56, 28
	s_cselect_b32 s37, s23, s3
	s_cselect_b32 s36, s22, s2
	s_cselect_b32 s35, s21, s55
	s_cselect_b32 s34, s53, s54
	v_lshl_add_u64 v[148:149], s[26:27], 0, v[136:137]
	s_add_i32 m0, s40, 0xc000
	ds_read_b128 v[168:171], v154
	ds_read_b128 v[172:175], v154 offset:1024
	ds_read_b128 v[176:179], v154 offset:2048
	ds_read_b128 v[180:183], v154 offset:3072
	ds_read_b128 v[184:187], v154 offset:4096
	ds_read_b128 v[188:191], v154 offset:5120
	ds_read_b128 v[192:195], v154 offset:6144
	ds_read_b128 v[196:199], v154 offset:7168
	global_load_lds_dwordx4 v[148:149], off
	v_lshl_add_u64 v[148:149], s[26:27], 0, v[138:139]
	s_add_i32 m0, s40, 0xe000
	s_nop 0
	global_load_lds_dwordx4 v[148:149], off
	s_waitcnt lgkmcnt(8)
	s_barrier
	s_waitcnt lgkmcnt(0)
	s_waitcnt lgkmcnt(0)
	v_mfma_f32_16x16x32_bf16 v[124:127], v[144:147], v[168:171], v[124:127]
	v_mfma_f32_16x16x32_bf16 v[120:123], v[160:163], v[168:171], v[120:123]
	v_mfma_f32_16x16x32_bf16 v[116:119], v[144:147], v[176:179], v[116:119]
	v_mfma_f32_16x16x32_bf16 v[112:115], v[160:163], v[176:179], v[112:115]
	v_mfma_f32_16x16x32_bf16 v[108:111], v[144:147], v[184:187], v[108:111]
	v_mfma_f32_16x16x32_bf16 v[100:103], v[160:163], v[184:187], v[100:103]
	v_mfma_f32_16x16x32_bf16 v[92:95], v[144:147], v[192:195], v[92:95]
	v_mfma_f32_16x16x32_bf16 v[80:83], v[160:163], v[192:195], v[80:83]
	v_mfma_f32_16x16x32_bf16 v[124:127], v[156:159], v[172:175], v[124:127]
	v_mfma_f32_16x16x32_bf16 v[120:123], v[164:167], v[172:175], v[120:123]
	v_mfma_f32_16x16x32_bf16 v[116:119], v[156:159], v[180:183], v[116:119]
	v_mfma_f32_16x16x32_bf16 v[112:115], v[164:167], v[180:183], v[112:115]
	v_mfma_f32_16x16x32_bf16 v[108:111], v[156:159], v[188:191], v[108:111]
	v_mfma_f32_16x16x32_bf16 v[100:103], v[164:167], v[188:191], v[100:103]
	v_mfma_f32_16x16x32_bf16 v[92:95], v[156:159], v[196:199], v[92:95]
	v_mfma_f32_16x16x32_bf16 v[80:83], v[164:167], v[196:199], v[80:83]
	s_barrier
	s_add_i32 s26, s48, s39
	v_lshl_add_u64 v[148:149], s[34:35], 0, v[130:131]
	s_mov_b32 m0, s26
	ds_read_b128 v[200:203], v155
	ds_read_b128 v[204:207], v155 offset:1024
	ds_read_b128 v[208:211], v155 offset:2048
	ds_read_b128 v[212:215], v155 offset:3072
	global_load_lds_dwordx4 v[148:149], off
	v_lshl_add_u64 v[216:217], s[34:35], 0, v[134:135]
	s_add_i32 m0, s26, 0x2000
	s_nop 0
	global_load_lds_dwordx4 v[216:217], off
	s_barrier
	s_waitcnt lgkmcnt(0)
	s_waitcnt lgkmcnt(0)
	v_mfma_f32_16x16x32_bf16 v[104:107], v[200:203], v[168:171], v[104:107]
	v_mfma_f32_16x16x32_bf16 v[96:99], v[208:211], v[168:171], v[96:99]
	v_mfma_f32_16x16x32_bf16 v[88:91], v[200:203], v[176:179], v[88:91]
	v_mfma_f32_16x16x32_bf16 v[84:87], v[208:211], v[176:179], v[84:87]
	v_mfma_f32_16x16x32_bf16 v[76:79], v[200:203], v[184:187], v[76:79]
	v_mfma_f32_16x16x32_bf16 v[72:75], v[208:211], v[184:187], v[72:75]
	v_mfma_f32_16x16x32_bf16 v[68:71], v[200:203], v[192:195], v[68:71]
	v_mfma_f32_16x16x32_bf16 v[64:67], v[208:211], v[192:195], v[64:67]
	v_mfma_f32_16x16x32_bf16 v[104:107], v[204:207], v[172:175], v[104:107]
	v_mfma_f32_16x16x32_bf16 v[96:99], v[212:215], v[172:175], v[96:99]
	v_mfma_f32_16x16x32_bf16 v[88:91], v[204:207], v[180:183], v[88:91]
	v_mfma_f32_16x16x32_bf16 v[84:87], v[212:215], v[180:183], v[84:87]
	v_mfma_f32_16x16x32_bf16 v[76:79], v[204:207], v[188:191], v[76:79]
	v_mfma_f32_16x16x32_bf16 v[72:75], v[212:215], v[188:191], v[72:75]
	v_mfma_f32_16x16x32_bf16 v[68:71], v[204:207], v[196:199], v[68:71]
	v_mfma_f32_16x16x32_bf16 v[64:67], v[212:215], v[196:199], v[64:67]
	s_mov_b32 m0, s40
	v_lshl_add_u64 v[218:219], s[36:37], 0, v[128:129]
	s_barrier
	ds_read_b128 v[168:171], v154 offset:16384
	ds_read_b128 v[172:175], v154 offset:17408
	ds_read_b128 v[176:179], v154 offset:18432
	ds_read_b128 v[180:183], v154 offset:19456
	ds_read_b128 v[184:187], v154 offset:20480
	ds_read_b128 v[188:191], v154 offset:21504
	ds_read_b128 v[192:195], v154 offset:22528
	ds_read_b128 v[196:199], v154 offset:23552
	global_load_lds_dwordx4 v[218:219], off
	v_lshl_add_u64 v[220:221], s[36:37], 0, v[132:133]
	s_mov_b32 m0, s41
	s_nop 0
	global_load_lds_dwordx4 v[220:221], off
	s_barrier
	s_waitcnt lgkmcnt(0)
	s_waitcnt lgkmcnt(0)
	v_mfma_f32_16x16x32_bf16 v[60:63], v[144:147], v[168:171], v[60:63]
	v_mfma_f32_16x16x32_bf16 v[56:59], v[160:163], v[168:171], v[56:59]
	v_mfma_f32_16x16x32_bf16 v[52:55], v[144:147], v[176:179], v[52:55]
	v_mfma_f32_16x16x32_bf16 v[48:51], v[160:163], v[176:179], v[48:51]
	v_mfma_f32_16x16x32_bf16 v[44:47], v[144:147], v[184:187], v[44:47]
	v_mfma_f32_16x16x32_bf16 v[36:39], v[160:163], v[184:187], v[36:39]
	v_mfma_f32_16x16x32_bf16 v[28:31], v[144:147], v[192:195], v[28:31]
	v_mfma_f32_16x16x32_bf16 v[16:19], v[160:163], v[192:195], v[16:19]
	v_mfma_f32_16x16x32_bf16 v[60:63], v[156:159], v[172:175], v[60:63]
	v_mfma_f32_16x16x32_bf16 v[56:59], v[164:167], v[172:175], v[56:59]
	v_mfma_f32_16x16x32_bf16 v[52:55], v[156:159], v[180:183], v[52:55]
	v_mfma_f32_16x16x32_bf16 v[48:51], v[164:167], v[180:183], v[48:51]
	v_mfma_f32_16x16x32_bf16 v[44:47], v[156:159], v[188:191], v[44:47]
	v_mfma_f32_16x16x32_bf16 v[36:39], v[164:167], v[188:191], v[36:39]
	v_mfma_f32_16x16x32_bf16 v[28:31], v[156:159], v[196:199], v[28:31]
	v_mfma_f32_16x16x32_bf16 v[16:19], v[164:167], v[196:199], v[16:19]
	s_barrier
; #define PG8_STAGE(bufoff, gbase, voff) do { _Pragma("unroll") for (int _i = 0; _i < 2; ++_i) \
;         __builtin_amdgcn_global_load_lds((const unsigned*)((const char*)(gbase) + (voff)[_i]), (LAS unsigned*)(lds + (bufoff) + ldsw + _i * 8192), 16, 0, 0); } while (0)
; #define PG8_LDA(dst, b, h) do { _Pragma("unroll") for (int m = 0; m < 4; ++m) _Pragma("unroll") for (int k = 0; k < 2; ++k) dst[m][k] = *(const LAS bf16x8*)(lds + PG8_SA(b, h) + aoff + m * 2048 + k * 1024); } while (0)
; #define PG8_LDB(dst, b, h) do { _Pragma("unroll") for (int n = 0; n < 2; ++n) _Pragma("unroll") for (int k = 0; k < 2; ++k) dst[n][k] = *(const LAS bf16x8*)(lds + PG8_SB(b, h) + boff + n * 2048 + k * 1024); } while (0)
; #define PG8_MMA(ai, bj, At, Bt) do { __builtin_amdgcn_s_setprio(1); _Pragma("unroll") for (int m = 0; m < 4; ++m) _Pragma("unroll") for (int n = 0; n < 2; ++n) _Pragma("unroll") for (int k = 0; k < 2; ++k) \
;         acc[ai][bj][m][n] = __builtin_amdgcn_mfma_f32_16x16x32_bf16(Bt[n][k], At[m][k], acc[ai][bj][m][n], 0, 0, 0); __builtin_amdgcn_s_setprio(0); } while (0)
; #define PG8_WAIT_V(n) asm volatile("s_waitcnt vmcnt(" #n ")" ::: "memory")
; #define PG8_WAIT_L(n) asm volatile("s_waitcnt lgkmcnt(" #n ")" ::: "memory")
; #define PG8_BAR __builtin_amdgcn_s_barrier()
; #define PG8_SCHED __builtin_amdgcn_sched_barrier(0)
; template <class Epi>
; DI void gemm_phase(LAS unsigned char* lds, const Gemm g, const StaticOrder& S, const Epi& E) {
;     ...
;             PG8_STAGE(PG8_SB(0, 1), b2 + hstepB, voffB);
;             PG8_WAIT_V(6); PG8_BAR; PG8_MMA(1, 1, At, B1); PG8_BAR;
;             PG8_LDB(B0, 1, 0); PG8_SCHED; PG8_LDA(At, 1, 0); PG8_STAGE(PG8_SA(0, 1), a2 + hstepA, voffA);
;             PG8_WAIT_L(8); PG8_BAR; PG8_WAIT_L(0); PG8_MMA(0, 0, At, B0); PG8_BAR; PG8_SCHED;
;             PG8_LDB(B1, 1, 1); PG8_STAGE(PG8_SB(1, 0), b3, voffB);
;             PG8_BAR; PG8_WAIT_L(0); PG8_MMA(0, 1, At, B1); PG8_BAR;
;             PG8_LDA(At, 1, 1); PG8_STAGE(PG8_SA(1, 0), a3, voffA);
;             PG8_BAR; PG8_WAIT_L(0); PG8_MMA(1, 0, At, B0); PG8_BAR; PG8_SCHED;
	s_add_u32 s26, s34, 0x80000
	s_addc_u32 s27, s35, 0
	s_add_i32 s57, s49, s39
	v_lshl_add_u64 v[144:145], s[26:27], 0, v[130:131]
	s_mov_b32 m0, s57
	s_nop 0
	global_load_lds_dwordx4 v[144:145], off
	v_lshl_add_u64 v[144:145], s[26:27], 0, v[134:135]
	s_add_i32 m0, s57, 0x2000
	s_nop 0
	global_load_lds_dwordx4 v[144:145], off
	s_waitcnt vmcnt(6)
	s_barrier
	v_mfma_f32_16x16x32_bf16 v[40:43], v[200:203], v[168:171], v[40:43]
	v_mfma_f32_16x16x32_bf16 v[32:35], v[208:211], v[168:171], v[32:35]
	v_mfma_f32_16x16x32_bf16 v[24:27], v[200:203], v[176:179], v[24:27]
	v_mfma_f32_16x16x32_bf16 v[20:23], v[208:211], v[176:179], v[20:23]
	v_mfma_f32_16x16x32_bf16 v[12:15], v[200:203], v[184:187], v[12:15]
	v_mfma_f32_16x16x32_bf16 v[8:11], v[208:211], v[184:187], v[8:11]
	v_mfma_f32_16x16x32_bf16 v[4:7], v[200:203], v[192:195], v[4:7]
	v_mfma_f32_16x16x32_bf16 v[0:3], v[208:211], v[192:195], v[0:3]
	v_mfma_f32_16x16x32_bf16 v[40:43], v[204:207], v[172:175], v[40:43]
	v_mfma_f32_16x16x32_bf16 v[32:35], v[212:215], v[172:175], v[32:35]
	v_mfma_f32_16x16x32_bf16 v[24:27], v[204:207], v[180:183], v[24:27]
	v_mfma_f32_16x16x32_bf16 v[20:23], v[212:215], v[180:183], v[20:23]
	v_mfma_f32_16x16x32_bf16 v[12:15], v[204:207], v[188:191], v[12:15]
	v_mfma_f32_16x16x32_bf16 v[8:11], v[212:215], v[188:191], v[8:11]
	v_mfma_f32_16x16x32_bf16 v[4:7], v[204:207], v[196:199], v[4:7]
	v_mfma_f32_16x16x32_bf16 v[0:3], v[212:215], v[196:199], v[0:3]
	s_add_i32 s57, 0, 0x18000
	v_add_u32_e32 v164, s57, v151
	s_barrier
	ds_read_b128 v[144:147], v164
	ds_read_b128 v[156:159], v164 offset:1024
	ds_read_b128 v[160:163], v164 offset:2048
	ds_read_b128 v[164:167], v164 offset:3072
	s_add_u32 s26, s36, 0x3b0000
	s_addc_u32 s27, s37, 0
	s_mov_b32 m0, s42
	v_lshl_add_u64 v[200:201], s[26:27], 0, v[128:129]
	ds_read_b128 v[168:171], v154 offset:32768
	ds_read_b128 v[172:175], v154 offset:33792
	ds_read_b128 v[176:179], v154 offset:34816
	ds_read_b128 v[180:183], v154 offset:35840
	ds_read_b128 v[184:187], v154 offset:36864
	ds_read_b128 v[188:191], v154 offset:37888
	ds_read_b128 v[192:195], v154 offset:38912
	ds_read_b128 v[196:199], v154 offset:39936
	global_load_lds_dwordx4 v[200:201], off
	v_lshl_add_u64 v[200:201], s[26:27], 0, v[132:133]
	s_mov_b32 m0, s43
	s_nop 0
	global_load_lds_dwordx4 v[200:201], off
	s_waitcnt lgkmcnt(8)
	s_barrier
	s_waitcnt lgkmcnt(0)
	s_waitcnt lgkmcnt(0)
	v_mfma_f32_16x16x32_bf16 v[124:127], v[144:147], v[168:171], v[124:127]
	v_mfma_f32_16x16x32_bf16 v[120:123], v[160:163], v[168:171], v[120:123]
	v_mfma_f32_16x16x32_bf16 v[116:119], v[144:147], v[176:179], v[116:119]
	v_mfma_f32_16x16x32_bf16 v[112:115], v[160:163], v[176:179], v[112:115]
	v_mfma_f32_16x16x32_bf16 v[108:111], v[144:147], v[184:187], v[108:111]
	v_mfma_f32_16x16x32_bf16 v[100:103], v[160:163], v[184:187], v[100:103]
	v_mfma_f32_16x16x32_bf16 v[92:95], v[144:147], v[192:195], v[92:95]
	v_mfma_f32_16x16x32_bf16 v[80:83], v[160:163], v[192:195], v[80:83]
	v_mfma_f32_16x16x32_bf16 v[124:127], v[156:159], v[172:175], v[124:127]
	v_mfma_f32_16x16x32_bf16 v[120:123], v[164:167], v[172:175], v[120:123]
	v_mfma_f32_16x16x32_bf16 v[116:119], v[156:159], v[180:183], v[116:119]
	v_mfma_f32_16x16x32_bf16 v[112:115], v[164:167], v[180:183], v[112:115]
	v_mfma_f32_16x16x32_bf16 v[108:111], v[156:159], v[188:191], v[108:111]
	v_mfma_f32_16x16x32_bf16 v[100:103], v[164:167], v[188:191], v[100:103]
	v_mfma_f32_16x16x32_bf16 v[92:95], v[156:159], v[196:199], v[92:95]
	v_mfma_f32_16x16x32_bf16 v[80:83], v[164:167], v[196:199], v[80:83]
	s_barrier
	s_add_i32 s36, 0, 0x1c000
	s_add_i32 s26, s57, s39
	v_add_u32_e32 v212, s36, v151
	v_lshl_add_u64 v[148:149], v[148:149], 0, s[4:5]
	s_mov_b32 m0, s26
	ds_read_b128 v[200:203], v212
	ds_read_b128 v[204:207], v212 offset:1024
	ds_read_b128 v[208:211], v212 offset:2048
	ds_read_b128 v[212:215], v212 offset:3072
	global_load_lds_dwordx4 v[148:149], off
	v_lshl_add_u64 v[148:149], v[216:217], 0, s[4:5]
	s_add_i32 m0, s26, 0x2000
	s_nop 0
	global_load_lds_dwordx4 v[148:149], off
	s_barrier
	s_waitcnt lgkmcnt(0)
	s_waitcnt lgkmcnt(0)
	v_mfma_f32_16x16x32_bf16 v[104:107], v[200:203], v[168:171], v[104:107]
	v_mfma_f32_16x16x32_bf16 v[96:99], v[208:211], v[168:171], v[96:99]
	v_mfma_f32_16x16x32_bf16 v[88:91], v[200:203], v[176:179], v[88:91]
	v_mfma_f32_16x16x32_bf16 v[84:87], v[208:211], v[176:179], v[84:87]
	v_mfma_f32_16x16x32_bf16 v[76:79], v[200:203], v[184:187], v[76:79]
	v_mfma_f32_16x16x32_bf16 v[72:75], v[208:211], v[184:187], v[72:75]
	v_mfma_f32_16x16x32_bf16 v[68:71], v[200:203], v[192:195], v[68:71]
	v_mfma_f32_16x16x32_bf16 v[64:67], v[208:211], v[192:195], v[64:67]
	v_mfma_f32_16x16x32_bf16 v[104:107], v[204:207], v[172:175], v[104:107]
	v_mfma_f32_16x16x32_bf16 v[96:99], v[212:215], v[172:175], v[96:99]
	v_mfma_f32_16x16x32_bf16 v[88:91], v[204:207], v[180:183], v[88:91]
	v_mfma_f32_16x16x32_bf16 v[84:87], v[212:215], v[180:183], v[84:87]
	v_mfma_f32_16x16x32_bf16 v[76:79], v[204:207], v[188:191], v[76:79]
	v_mfma_f32_16x16x32_bf16 v[72:75], v[212:215], v[188:191], v[72:75]
	v_mfma_f32_16x16x32_bf16 v[68:71], v[204:207], v[196:199], v[68:71]
	v_mfma_f32_16x16x32_bf16 v[64:67], v[212:215], v[196:199], v[64:67]
	s_mov_b32 m0, s45
	v_lshl_add_u64 v[148:149], v[218:219], 0, s[4:5]
	s_barrier
	ds_read_b128 v[168:171], v154 offset:49152
	ds_read_b128 v[172:175], v154 offset:50176
	ds_read_b128 v[176:179], v154 offset:51200
	ds_read_b128 v[180:183], v154 offset:52224
	ds_read_b128 v[184:187], v154 offset:53248
	ds_read_b128 v[188:191], v154 offset:54272
	ds_read_b128 v[192:195], v154 offset:55296
	ds_read_b128 v[196:199], v154 offset:56320
	global_load_lds_dwordx4 v[148:149], off
	v_lshl_add_u64 v[148:149], v[220:221], 0, s[4:5]
	s_mov_b32 m0, s46
	s_nop 0
	global_load_lds_dwordx4 v[148:149], off
	s_barrier
; #define PG8_STAGE(bufoff, gbase, voff) do { _Pragma("unroll") for (int _i = 0; _i < 2; ++_i) \
;         __builtin_amdgcn_global_load_lds((const unsigned*)((const char*)(gbase) + (voff)[_i]), (LAS unsigned*)(lds + (bufoff) + ldsw + _i * 8192), 16, 0, 0); } while (0)
; #define PG8_LDA(dst, b, h) do { _Pragma("unroll") for (int m = 0; m < 4; ++m) _Pragma("unroll") for (int k = 0; k < 2; ++k) dst[m][k] = *(const LAS bf16x8*)(lds + PG8_SA(b, h) + aoff + m * 2048 + k * 1024); } while (0)
; #define PG8_LDB(dst, b, h) do { _Pragma("unroll") for (int n = 0; n < 2; ++n) _Pragma("unroll") for (int k = 0; k < 2; ++k) dst[n][k] = *(const LAS bf16x8*)(lds + PG8_SB(b, h) + boff + n * 2048 + k * 1024); } while (0)
; #define PG8_MMA(ai, bj, At, Bt) do { __builtin_amdgcn_s_setprio(1); _Pragma("unroll") for (int m = 0; m < 4; ++m) _Pragma("unroll") for (int n = 0; n < 2; ++n) _Pragma("unroll") for (int k = 0; k < 2; ++k) \
;         acc[ai][bj][m][n] = __builtin_amdgcn_mfma_f32_16x16x32_bf16(Bt[n][k], At[m][k], acc[ai][bj][m][n], 0, 0, 0); __builtin_amdgcn_s_setprio(0); } while (0)
; #define PG8_WAIT_V(n) asm volatile("s_waitcnt vmcnt(" #n ")" ::: "memory")
; #define PG8_WAIT_L(n) asm volatile("s_waitcnt lgkmcnt(" #n ")" ::: "memory")
; template <class Epi>
; DI void gemm_phase(LAS unsigned char* lds, const Gemm g, const StaticOrder& S, const Epi& E) {
;     ...
;             PG8_LDB(B1, 1, 1); PG8_STAGE(PG8_SB(1, 0), b3, voffB);
;             PG8_BAR; PG8_WAIT_L(0); PG8_MMA(0, 1, At, B1); PG8_BAR;
;             PG8_LDA(At, 1, 1); PG8_STAGE(PG8_SA(1, 0), a3, voffA);
;             PG8_BAR; PG8_WAIT_L(0); PG8_MMA(1, 0, At, B0); PG8_BAR; PG8_SCHED;
;             PG8_STAGE(PG8_SB(1, 1), b3 + hstepB, voffB);
;             PG8_WAIT_V(6); PG8_BAR; PG8_MMA(1, 1, At, B1); PG8_BAR;
;     DI void operator()(const f32x4 (&acc)[2][2][4][2], const Unit& u, int wr, int wc, int fr, int fq) const {
;         const int row0 = u.pm * BM + wr * 64 + fr, col0 = u.pn * BM + wc * 32 + 4 * fq;
; #pragma unroll
;         for (int ai = 0; ai < 2; ++ai) {
;             f32x4 xv[4][2][2];
; #pragma unroll
;             for (int m = 0; m < 4; ++m) { const size_t off = (size_t)(row0 + ai * HALF + m * 16) * DM + col0;
; #pragma unroll
;                 for (int bj = 0; bj < 2; ++bj)
; #pragma unroll
;                     for (int n = 0; n < 2; ++n) xv[m][bj][n] = *(const f32x4*)(X + off + bj * HALF + n * 16); }
	s_waitcnt lgkmcnt(0)
	s_waitcnt lgkmcnt(0)
	v_mfma_f32_16x16x32_bf16 v[60:63], v[144:147], v[168:171], v[60:63]
	v_mfma_f32_16x16x32_bf16 v[56:59], v[160:163], v[168:171], v[56:59]
	v_mfma_f32_16x16x32_bf16 v[52:55], v[144:147], v[176:179], v[52:55]
	v_mfma_f32_16x16x32_bf16 v[48:51], v[160:163], v[176:179], v[48:51]
	v_mfma_f32_16x16x32_bf16 v[44:47], v[144:147], v[184:187], v[44:47]
	v_mfma_f32_16x16x32_bf16 v[36:39], v[160:163], v[184:187], v[36:39]
	v_mfma_f32_16x16x32_bf16 v[28:31], v[144:147], v[192:195], v[28:31]
	v_mfma_f32_16x16x32_bf16 v[16:19], v[160:163], v[192:195], v[16:19]
	v_mfma_f32_16x16x32_bf16 v[60:63], v[156:159], v[172:175], v[60:63]
	v_mfma_f32_16x16x32_bf16 v[56:59], v[164:167], v[172:175], v[56:59]
	v_mfma_f32_16x16x32_bf16 v[52:55], v[156:159], v[180:183], v[52:55]
	v_mfma_f32_16x16x32_bf16 v[48:51], v[164:167], v[180:183], v[48:51]
	v_mfma_f32_16x16x32_bf16 v[44:47], v[156:159], v[188:191], v[44:47]
	v_mfma_f32_16x16x32_bf16 v[36:39], v[164:167], v[188:191], v[36:39]
	v_mfma_f32_16x16x32_bf16 v[28:31], v[156:159], v[196:199], v[28:31]
	v_mfma_f32_16x16x32_bf16 v[16:19], v[164:167], v[196:199], v[16:19]
	s_barrier
	s_add_u32 s26, s34, 0x80080
	s_addc_u32 s27, s35, 0
	s_add_i32 s34, s36, s39
	v_lshl_add_u64 v[144:145], s[26:27], 0, v[130:131]
	s_mov_b32 m0, s34
	s_nop 0
	global_load_lds_dwordx4 v[144:145], off
	v_lshl_add_u64 v[144:145], s[26:27], 0, v[134:135]
	s_add_i32 m0, s34, 0x2000
	s_nop 0
	global_load_lds_dwordx4 v[144:145], off
	s_waitcnt vmcnt(6)
	s_barrier
	v_mfma_f32_16x16x32_bf16 v[40:43], v[200:203], v[168:171], v[40:43]
	v_mfma_f32_16x16x32_bf16 v[32:35], v[208:211], v[168:171], v[32:35]
	v_mfma_f32_16x16x32_bf16 v[24:27], v[200:203], v[176:179], v[24:27]
	v_mfma_f32_16x16x32_bf16 v[20:23], v[208:211], v[176:179], v[20:23]
	v_mfma_f32_16x16x32_bf16 v[12:15], v[200:203], v[184:187], v[12:15]
	v_mfma_f32_16x16x32_bf16 v[8:11], v[208:211], v[184:187], v[8:11]
	v_mfma_f32_16x16x32_bf16 v[4:7], v[200:203], v[192:195], v[4:7]
	v_mfma_f32_16x16x32_bf16 v[0:3], v[208:211], v[192:195], v[0:3]
	v_mfma_f32_16x16x32_bf16 v[40:43], v[204:207], v[172:175], v[40:43]
	v_mfma_f32_16x16x32_bf16 v[32:35], v[212:215], v[172:175], v[32:35]
	v_mfma_f32_16x16x32_bf16 v[24:27], v[204:207], v[180:183], v[24:27]
	v_mfma_f32_16x16x32_bf16 v[20:23], v[212:215], v[180:183], v[20:23]
	v_mfma_f32_16x16x32_bf16 v[12:15], v[204:207], v[188:191], v[12:15]
	v_mfma_f32_16x16x32_bf16 v[8:11], v[212:215], v[188:191], v[8:11]
	v_mfma_f32_16x16x32_bf16 v[4:7], v[204:207], v[196:199], v[4:7]
	v_mfma_f32_16x16x32_bf16 v[0:3], v[212:215], v[196:199], v[0:3]
	s_add_i32 s56, s56, 2
	s_add_u32 s54, s54, 0x100
	s_addc_u32 s55, s55, 0
	s_cmp_gt_u32 s56, 29
	s_mov_b64 s[26:27], s[2:3]
	s_barrier
	s_cbranch_scc0 .LBB0_705
	v_lshl_add_u32 v204, s51, 8, v150
	v_lshl_or_b32 v144, s52, 8, v152
	v_ashrrev_i32_e32 v205, 31, v204
	v_ashrrev_i32_e32 v145, 31, v144
	v_lshlrev_b64 v[148:149], 13, v[204:205]
	v_or_b32_e32 v172, 16, v204
	v_or_b32_e32 v188, 32, v204
	v_or_b32_e32 v204, 48, v204
	v_lshlrev_b64 v[144:145], 2, v[144:145]
	v_ashrrev_i32_e32 v173, 31, v172
	v_ashrrev_i32_e32 v189, 31, v188
	v_ashrrev_i32_e32 v205, 31, v204
	v_lshl_add_u64 v[146:147], s[12:13], 0, v[144:145]
	v_lshlrev_b64 v[220:221], 13, v[172:173]
	v_lshlrev_b64 v[222:223], 13, v[188:189]
	v_lshlrev_b64 v[224:225], 13, v[204:205]
	v_lshl_add_u64 v[168:169], v[146:147], 0, v[148:149]
	v_lshl_add_u64 v[184:185], v[146:147], 0, v[220:221]
	v_lshl_add_u64 v[200:201], v[146:147], 0, v[222:223]
	v_lshl_add_u64 v[216:217], v[146:147], 0, v[224:225]
	global_load_dwordx4 v[156:159], v[168:169], off
	global_load_dwordx4 v[160:163], v[168:169], off offset:64
	global_load_dwordx4 v[164:167], v[168:169], off offset:512
	s_nop 0
	global_load_dwordx4 v[168:171], v[168:169], off offset:576
	s_nop 0
	global_load_dwordx4 v[172:175], v[184:185], off
	global_load_dwordx4 v[176:179], v[184:185], off offset:64
	global_load_dwordx4 v[180:183], v[184:185], off offset:512
	s_nop 0
	global_load_dwordx4 v[184:187], v[184:185], off offset:576
	s_nop 0
	global_load_dwordx4 v[188:191], v[200:201], off
	global_load_dwordx4 v[192:195], v[200:201], off offset:64
	global_load_dwordx4 v[196:199], v[200:201], off offset:512
	s_nop 0
	global_load_dwordx4 v[200:203], v[200:201], off offset:576
	s_nop 0
	global_load_dwordx4 v[204:207], v[216:217], off
	global_load_dwordx4 v[208:211], v[216:217], off offset:64
	global_load_dwordx4 v[212:215], v[216:217], off offset:512
	s_nop 0
	global_load_dwordx4 v[216:219], v[216:217], off offset:576
	v_lshl_add_u64 v[226:227], s[28:29], 0, v[148:149]
	v_lshl_add_u64 v[224:225], s[28:29], 0, v[224:225]
	v_lshl_add_u64 v[226:227], v[226:227], 0, v[144:145]
	v_lshl_add_u64 v[220:221], s[28:29], 0, v[220:221]
	v_lshl_add_u64 v[222:223], s[28:29], 0, v[222:223]
	v_lshl_add_u64 v[224:225], v[224:225], 0, v[144:145]
	v_lshl_add_u64 v[220:221], v[220:221], 0, v[144:145]
	v_lshl_add_u64 v[222:223], v[222:223], 0, v[144:145]
	s_and_b64 vcc, exec, s[0:1]
	s_mov_b32 s52, s20
	s_mov_b32 s51, s50
	s_mov_b64 s[34:35], s[24:25]
	s_mov_b64 s[26:27], s[22:23]
	s_waitcnt vmcnt(0)
; #define PG8_WAIT_V(n) asm volatile("s_waitcnt vmcnt(" #n ")" ::: "memory")
; #define PG8_BAR __builtin_amdgcn_s_barrier()
; template <class Epi>
; DI void gemm_phase(LAS unsigned char* lds, const Gemm g, const StaticOrder& S, const Epi& E) {
;     ...
;     PG8_WAIT_V(0);
;     if (wr == 0) PG8_BAR;
;     DI void operator()(const f32x4 (&acc)[2][2][4][2], const Unit& u, int wr, int wc, int fr, int fq) const {
;         const int row0 = u.pm * BM + wr * 64 + fr, col0 = u.pn * BM + wc * 32 + 4 * fq;
; #pragma unroll
;         for (int ai = 0; ai < 2; ++ai) {
;             f32x4 xv[4][2][2];
; #pragma unroll
;             for (int m = 0; m < 4; ++m) { const size_t off = (size_t)(row0 + ai * HALF + m * 16) * DM + col0;
; #pragma unroll
;                 for (int bj = 0; bj < 2; ++bj)
; #pragma unroll
;                     for (int n = 0; n < 2; ++n) xv[m][bj][n] = *(const f32x4*)(X + off + bj * HALF + n * 16); }
; #pragma unroll
;             for (int m = 0; m < 4; ++m) { const size_t off = (size_t)(row0 + ai * HALF + m * 16) * DM + col0;
; #pragma unroll
;                 for (int bj = 0; bj < 2; ++bj)
; #pragma unroll
;                     for (int n = 0; n < 2; ++n) *(f32x4*)(C + off + bj * HALF + n * 16) = acc[ai][bj][m][n] + xv[m][bj][n]; }
;             asm volatile("" ::: "memory");
;         }
	v_pk_add_f32 v[126:127], v[126:127], v[158:159]
	v_pk_add_f32 v[124:125], v[124:125], v[156:157]
	v_pk_add_f32 v[122:123], v[122:123], v[162:163]
	v_pk_add_f32 v[120:121], v[120:121], v[160:161]
	v_pk_add_f32 v[106:107], v[106:107], v[166:167]
	v_pk_add_f32 v[70:71], v[70:71], v[214:215]
	v_pk_add_f32 v[68:69], v[68:69], v[212:213]
	v_pk_add_f32 v[66:67], v[66:67], v[218:219]
	v_pk_add_f32 v[64:65], v[64:65], v[216:217]
	v_pk_add_f32 v[104:105], v[104:105], v[164:165]
	v_pk_add_f32 v[98:99], v[98:99], v[170:171]
	v_pk_add_f32 v[96:97], v[96:97], v[168:169]
	v_pk_add_f32 v[118:119], v[118:119], v[174:175]
	v_pk_add_f32 v[116:117], v[116:117], v[172:173]
	v_pk_add_f32 v[114:115], v[114:115], v[178:179]
	v_pk_add_f32 v[112:113], v[112:113], v[176:177]
	v_pk_add_f32 v[90:91], v[90:91], v[182:183]
	v_pk_add_f32 v[88:89], v[88:89], v[180:181]
	v_pk_add_f32 v[86:87], v[86:87], v[186:187]
	v_pk_add_f32 v[84:85], v[84:85], v[184:185]
	v_pk_add_f32 v[110:111], v[110:111], v[190:191]
	v_pk_add_f32 v[108:109], v[108:109], v[188:189]
	v_pk_add_f32 v[102:103], v[102:103], v[194:195]
	v_pk_add_f32 v[100:101], v[100:101], v[192:193]
	v_pk_add_f32 v[78:79], v[78:79], v[198:199]
	v_pk_add_f32 v[76:77], v[76:77], v[196:197]
	v_pk_add_f32 v[74:75], v[74:75], v[202:203]
	v_pk_add_f32 v[72:73], v[72:73], v[200:201]
	v_pk_add_f32 v[94:95], v[94:95], v[206:207]
	v_pk_add_f32 v[92:93], v[92:93], v[204:205]
	v_pk_add_f32 v[82:83], v[82:83], v[210:211]
	v_pk_add_f32 v[80:81], v[80:81], v[208:209]
	global_store_dwordx4 v[226:227], v[124:127], off
	global_store_dwordx4 v[226:227], v[120:123], off offset:64
	global_store_dwordx4 v[226:227], v[104:107], off offset:512
	global_store_dwordx4 v[226:227], v[96:99], off offset:576
	global_store_dwordx4 v[220:221], v[116:119], off
	global_store_dwordx4 v[220:221], v[112:115], off offset:64
	global_store_dwordx4 v[220:221], v[88:91], off offset:512
	global_store_dwordx4 v[220:221], v[84:87], off offset:576
	global_store_dwordx4 v[222:223], v[108:111], off
	global_store_dwordx4 v[222:223], v[100:103], off offset:64
	global_store_dwordx4 v[222:223], v[76:79], off offset:512
	global_store_dwordx4 v[222:223], v[72:75], off offset:576
	global_store_dwordx4 v[224:225], v[92:95], off
	global_store_dwordx4 v[224:225], v[80:83], off offset:64
	global_store_dwordx4 v[224:225], v[68:71], off offset:512
	global_store_dwordx4 v[224:225], v[64:67], off offset:576
	v_lshl_add_u64 v[156:157], v[148:149], 0, s[8:9]
	v_lshl_add_u64 v[158:159], v[148:149], 0, s[14:15]
	v_lshl_add_u64 v[160:161], v[148:149], 0, s[16:17]
	v_lshl_add_u64 v[148:149], v[148:149], 0, s[18:19]
	v_lshl_add_u64 v[80:81], v[146:147], 0, v[156:157]
	v_lshl_add_u64 v[92:93], v[146:147], 0, v[158:159]
	v_lshl_add_u64 v[108:109], v[146:147], 0, v[160:161]
	v_lshl_add_u64 v[124:125], v[146:147], 0, v[148:149]
	global_load_dwordx4 v[64:67], v[80:81], off
	global_load_dwordx4 v[68:71], v[80:81], off offset:64
	global_load_dwordx4 v[72:75], v[80:81], off offset:512
	global_load_dwordx4 v[76:79], v[80:81], off offset:576
	s_nop 0
	global_load_dwordx4 v[80:83], v[92:93], off
	global_load_dwordx4 v[84:87], v[92:93], off offset:64
	global_load_dwordx4 v[88:91], v[92:93], off offset:512
	s_nop 0
	global_load_dwordx4 v[92:95], v[92:93], off offset:576
	s_nop 0
	global_load_dwordx4 v[96:99], v[108:109], off
	global_load_dwordx4 v[100:103], v[108:109], off offset:64
	global_load_dwordx4 v[104:107], v[108:109], off offset:512
	s_nop 0
	global_load_dwordx4 v[108:111], v[108:109], off offset:576
	s_nop 0
	global_load_dwordx4 v[112:115], v[124:125], off
	global_load_dwordx4 v[116:119], v[124:125], off offset:64
	global_load_dwordx4 v[120:123], v[124:125], off offset:512
	s_nop 0
	global_load_dwordx4 v[124:127], v[124:125], off offset:576
	v_lshl_add_u64 v[146:147], s[28:29], 0, v[156:157]
	v_lshl_add_u64 v[156:157], s[28:29], 0, v[158:159]
	v_lshl_add_u64 v[158:159], s[28:29], 0, v[160:161]
	v_lshl_add_u64 v[148:149], s[28:29], 0, v[148:149]
	v_lshl_add_u64 v[146:147], v[146:147], 0, v[144:145]
	v_lshl_add_u64 v[156:157], v[156:157], 0, v[144:145]
	v_lshl_add_u64 v[158:159], v[158:159], 0, v[144:145]
	v_lshl_add_u64 v[144:145], v[148:149], 0, v[144:145]
	s_waitcnt vmcnt(0)
	v_pk_add_f32 v[62:63], v[62:63], v[66:67]
	v_pk_add_f32 v[60:61], v[60:61], v[64:65]
	v_pk_add_f32 v[58:59], v[58:59], v[70:71]
	v_pk_add_f32 v[56:57], v[56:57], v[68:69]
	v_pk_add_f32 v[42:43], v[42:43], v[74:75]
	v_pk_add_f32 v[40:41], v[40:41], v[72:73]
	v_pk_add_f32 v[2:3], v[2:3], v[126:127]
	v_pk_add_f32 v[0:1], v[0:1], v[124:125]
	v_pk_add_f32 v[34:35], v[34:35], v[78:79]
	v_pk_add_f32 v[32:33], v[32:33], v[76:77]
	v_pk_add_f32 v[54:55], v[54:55], v[82:83]
	v_pk_add_f32 v[52:53], v[52:53], v[80:81]
	v_pk_add_f32 v[50:51], v[50:51], v[86:87]
	v_pk_add_f32 v[48:49], v[48:49], v[84:85]
	v_pk_add_f32 v[26:27], v[26:27], v[90:91]
	v_pk_add_f32 v[24:25], v[24:25], v[88:89]
	v_pk_add_f32 v[22:23], v[22:23], v[94:95]
	v_pk_add_f32 v[20:21], v[20:21], v[92:93]
	v_pk_add_f32 v[46:47], v[46:47], v[98:99]
	v_pk_add_f32 v[44:45], v[44:45], v[96:97]
	v_pk_add_f32 v[38:39], v[38:39], v[102:103]
	v_pk_add_f32 v[36:37], v[36:37], v[100:101]
	v_pk_add_f32 v[14:15], v[14:15], v[106:107]
	v_pk_add_f32 v[12:13], v[12:13], v[104:105]
	v_pk_add_f32 v[10:11], v[10:11], v[110:111]
	v_pk_add_f32 v[8:9], v[8:9], v[108:109]
	v_pk_add_f32 v[30:31], v[30:31], v[114:115]
	v_pk_add_f32 v[28:29], v[28:29], v[112:113]
	v_pk_add_f32 v[18:19], v[18:19], v[118:119]
	v_pk_add_f32 v[16:17], v[16:17], v[116:117]
	v_pk_add_f32 v[6:7], v[6:7], v[122:123]
	v_pk_add_f32 v[4:5], v[4:5], v[120:121]
	global_store_dwordx4 v[146:147], v[60:63], off
	global_store_dwordx4 v[146:147], v[56:59], off offset:64
	global_store_dwordx4 v[146:147], v[40:43], off offset:512
	global_store_dwordx4 v[146:147], v[32:35], off offset:576
	global_store_dwordx4 v[156:157], v[52:55], off
	global_store_dwordx4 v[156:157], v[48:51], off offset:64
	global_store_dwordx4 v[156:157], v[24:27], off offset:512
	global_store_dwordx4 v[156:157], v[20:23], off offset:576
	global_store_dwordx4 v[158:159], v[44:47], off
	global_store_dwordx4 v[158:159], v[36:39], off offset:64
	global_store_dwordx4 v[158:159], v[12:15], off offset:512
	global_store_dwordx4 v[158:159], v[8:11], off offset:576
	global_store_dwordx4 v[144:145], v[28:31], off
	global_store_dwordx4 v[144:145], v[16:19], off offset:64
	global_store_dwordx4 v[144:145], v[4:7], off offset:512
	global_store_dwordx4 v[144:145], v[0:3], off offset:576
	s_cbranch_vccz .LBB0_696
	s_waitcnt vmcnt(0)
	s_cmpk_gt_u32 s7, 0xff
	s_cbranch_scc1 .LBB0_709
	s_barrier

; template <int LO, int HI>
; __global__ void __launch_bounds__(512) fwd_kernel(Params P) {
;     ...
;         run_phase<5>(P, smem);
;     } else {
;         run_phase<LO>(P, smem);
;     }
; }
.LBB0_710:
	s_setprio 0
	s_endpgm
